# convert_weights (layers 1-3): W-tile gather loops re-issued with 16 global loads in flight (were 2) and counted vmcnt waits
# speedup vs baseline: 1.0041x; 1.0041x over previous
; __device__ __forceinline__ void transpose_item(const float* W, int K, int N, bf16_t* WT, LAS float* scr, int item, int lane) {
;     const int nblk = N / 32, kb = item / nblk, nb = item % nblk, k0 = 64 * kb, n0 = 32 * nb;
; #pragma unroll 8
;     for (int i = 0; i < 32; ++i) { const int kk = 2 * i + (lane >> 5); scr[kk * 33 + (lane & 31)] = W[(size_t)(k0 + kk) * N + n0 + (lane & 31)]; }
;     asm volatile("s_waitcnt lgkmcnt(0)" ::: "memory");
; __device__ __forceinline__ void convert_weights(const Params& p, int l, unsigned char* lds) {
;     ...
;         transpose_item(p.in[I_WOUT] + (size_t)l * 1024 * 1024, 1024, 1024, wout, scr, r, lane);
.Lcw_gather1:
	s_lshl_b32 s13, s10, 1
	s_lshl_b32 s12, s2, 1
	v_or_b32_e32 v64, s13, v18
	v_or_b32_e32 v65, s12, v5
	v_or_b32_e32 v66, s13, v2
	v_or_b32_e32 v67, s12, v3
	v_add_u32_e32 v72, 0, v64
	v_mov_b32_e32 v73, v1
	v_lshlrev_b64 v[68:69], 12, v[72:73]
	v_lshl_add_u64 v[68:69], v[16:17], 0, v[68:69]
	global_load_dword v48, v[68:69], off
	v_add_u32_e32 v72, 0, v65
	v_mov_b32_e32 v73, v1
	v_lshlrev_b64 v[70:71], 12, v[72:73]
	v_lshl_add_u64 v[70:71], v[16:17], 0, v[70:71]
	global_load_dword v49, v[70:71], off
	v_add_u32_e32 v72, 4, v64
	v_mov_b32_e32 v73, v1
	v_lshlrev_b64 v[68:69], 12, v[72:73]
	v_lshl_add_u64 v[68:69], v[16:17], 0, v[68:69]
	global_load_dword v50, v[68:69], off
	v_add_u32_e32 v72, 4, v65
	v_mov_b32_e32 v73, v1
	v_lshlrev_b64 v[70:71], 12, v[72:73]
	v_lshl_add_u64 v[70:71], v[16:17], 0, v[70:71]
	global_load_dword v51, v[70:71], off
	v_add_u32_e32 v72, 8, v64
	v_mov_b32_e32 v73, v1
	v_lshlrev_b64 v[68:69], 12, v[72:73]
	v_lshl_add_u64 v[68:69], v[16:17], 0, v[68:69]
	global_load_dword v52, v[68:69], off
	v_add_u32_e32 v72, 8, v65
	v_mov_b32_e32 v73, v1
	v_lshlrev_b64 v[70:71], 12, v[72:73]
	v_lshl_add_u64 v[70:71], v[16:17], 0, v[70:71]
	global_load_dword v53, v[70:71], off
	v_add_u32_e32 v72, 12, v64
	v_mov_b32_e32 v73, v1
	v_lshlrev_b64 v[68:69], 12, v[72:73]
	v_lshl_add_u64 v[68:69], v[16:17], 0, v[68:69]
	global_load_dword v54, v[68:69], off
	v_add_u32_e32 v72, 12, v65
	v_mov_b32_e32 v73, v1
	v_lshlrev_b64 v[70:71], 12, v[72:73]
	v_lshl_add_u64 v[70:71], v[16:17], 0, v[70:71]
	global_load_dword v55, v[70:71], off
	v_add_u32_e32 v72, 16, v64
	v_mov_b32_e32 v73, v1
	v_lshlrev_b64 v[68:69], 12, v[72:73]
	v_lshl_add_u64 v[68:69], v[16:17], 0, v[68:69]
	global_load_dword v56, v[68:69], off
	v_add_u32_e32 v72, 16, v65
	v_mov_b32_e32 v73, v1
	v_lshlrev_b64 v[70:71], 12, v[72:73]
	v_lshl_add_u64 v[70:71], v[16:17], 0, v[70:71]
	global_load_dword v57, v[70:71], off
	v_add_u32_e32 v72, 20, v64
	v_mov_b32_e32 v73, v1
	v_lshlrev_b64 v[68:69], 12, v[72:73]
	v_lshl_add_u64 v[68:69], v[16:17], 0, v[68:69]
	global_load_dword v58, v[68:69], off
	v_add_u32_e32 v72, 20, v65
	v_mov_b32_e32 v73, v1
	v_lshlrev_b64 v[70:71], 12, v[72:73]
	v_lshl_add_u64 v[70:71], v[16:17], 0, v[70:71]
	global_load_dword v59, v[70:71], off
	v_add_u32_e32 v72, 24, v64
	v_mov_b32_e32 v73, v1
	v_lshlrev_b64 v[68:69], 12, v[72:73]
	v_lshl_add_u64 v[68:69], v[16:17], 0, v[68:69]
	global_load_dword v60, v[68:69], off
	v_add_u32_e32 v72, 24, v65
	v_mov_b32_e32 v73, v1
	v_lshlrev_b64 v[70:71], 12, v[72:73]
	v_lshl_add_u64 v[70:71], v[16:17], 0, v[70:71]
	global_load_dword v61, v[70:71], off
	v_add_u32_e32 v72, 28, v64
	v_mov_b32_e32 v73, v1
	v_lshlrev_b64 v[68:69], 12, v[72:73]
	v_lshl_add_u64 v[68:69], v[16:17], 0, v[68:69]
	global_load_dword v62, v[68:69], off
	v_add_u32_e32 v72, 28, v65
	v_mov_b32_e32 v73, v1
	v_lshlrev_b64 v[70:71], 12, v[72:73]
	v_lshl_add_u64 v[70:71], v[16:17], 0, v[70:71]
	global_load_dword v63, v[70:71], off
	v_add_u32_e32 v72, 0, v66
	v_mad_u64_u32 v[68:69], s[14:15], v72, s91, v[4:5]
	s_waitcnt vmcnt(15)
	ds_write_b32 v68, v48
	v_add_u32_e32 v72, 0, v67
	v_mad_u64_u32 v[70:71], s[14:15], v72, s91, v[4:5]
	s_waitcnt vmcnt(14)
	ds_write_b32 v70, v49
	v_add_u32_e32 v72, 4, v66
	v_mad_u64_u32 v[68:69], s[14:15], v72, s91, v[4:5]
	s_waitcnt vmcnt(13)
	ds_write_b32 v68, v50
	v_add_u32_e32 v72, 4, v67
	v_mad_u64_u32 v[70:71], s[14:15], v72, s91, v[4:5]
	s_waitcnt vmcnt(12)
	ds_write_b32 v70, v51
	v_add_u32_e32 v72, 8, v66
	v_mad_u64_u32 v[68:69], s[14:15], v72, s91, v[4:5]
	s_waitcnt vmcnt(11)
	ds_write_b32 v68, v52
	v_add_u32_e32 v72, 8, v67
	v_mad_u64_u32 v[70:71], s[14:15], v72, s91, v[4:5]
	s_waitcnt vmcnt(10)
	ds_write_b32 v70, v53
	v_add_u32_e32 v72, 12, v66
	v_mad_u64_u32 v[68:69], s[14:15], v72, s91, v[4:5]
	s_waitcnt vmcnt(9)
	ds_write_b32 v68, v54
	v_add_u32_e32 v72, 12, v67
	v_mad_u64_u32 v[70:71], s[14:15], v72, s91, v[4:5]
	s_waitcnt vmcnt(8)
	ds_write_b32 v70, v55
	v_add_u32_e32 v72, 16, v66
	v_mad_u64_u32 v[68:69], s[14:15], v72, s91, v[4:5]
	s_waitcnt vmcnt(7)
	ds_write_b32 v68, v56
	v_add_u32_e32 v72, 16, v67
	v_mad_u64_u32 v[70:71], s[14:15], v72, s91, v[4:5]
	s_waitcnt vmcnt(6)
	ds_write_b32 v70, v57
	v_add_u32_e32 v72, 20, v66
	v_mad_u64_u32 v[68:69], s[14:15], v72, s91, v[4:5]
	s_waitcnt vmcnt(5)
	ds_write_b32 v68, v58
	v_add_u32_e32 v72, 20, v67
	v_mad_u64_u32 v[70:71], s[14:15], v72, s91, v[4:5]
	s_waitcnt vmcnt(4)
	ds_write_b32 v70, v59
	v_add_u32_e32 v72, 24, v66
	v_mad_u64_u32 v[68:69], s[14:15], v72, s91, v[4:5]
	s_waitcnt vmcnt(3)
	ds_write_b32 v68, v60
	v_add_u32_e32 v72, 24, v67
	v_mad_u64_u32 v[70:71], s[14:15], v72, s91, v[4:5]
	s_waitcnt vmcnt(2)
	ds_write_b32 v70, v61
	v_add_u32_e32 v72, 28, v66
	v_mad_u64_u32 v[68:69], s[14:15], v72, s91, v[4:5]
	s_waitcnt vmcnt(1)
	ds_write_b32 v68, v62
	v_add_u32_e32 v72, 28, v67
	v_mad_u64_u32 v[70:71], s[14:15], v72, s91, v[4:5]
	s_waitcnt vmcnt(0)
	ds_write_b32 v70, v63
	s_add_i32 s10, s10, 16
	s_add_i32 s2, s2, 16
	s_add_i32 s11, s11, -16
	s_cmp_lg_u32 s11, 0
	s_cbranch_scc1 .Lcw_gather1
; #define LAS __attribute__((address_space(3)))
; __device__ __forceinline__ unsigned pk2(float lo, float hi) { f32x2 v = {lo, hi}; hbf16x2 b = __builtin_convertvector(v, hbf16x2); return __builtin_bit_cast(unsigned, b); }
; __device__ __forceinline__ void transpose_item(const float* W, int K, int N, bf16_t* WT, LAS float* scr, int item, int lane) {
;     ...
;     const int c = lane & 7;
; #pragma unroll
;     for (int j = 0; j < 4; ++j) { const int n = (lane >> 3) + 8 * j; const LAS float* s = scr + (8 * c) * 33 + n;
;         u32x4 o; o.x = pk2(s[0 * 33], s[1 * 33]); o.y = pk2(s[2 * 33], s[3 * 33]); o.z = pk2(s[4 * 33], s[5 * 33]); o.w = pk2(s[6 * 33], s[7 * 33]);
;         *(u32x4*)(WT + (size_t)(n0 + n) * K + k0 + 8 * c) = o; }
;     asm volatile("s_waitcnt lgkmcnt(0)" ::: "memory");
	s_waitcnt lgkmcnt(0)
	ds_read2_b32 v[30:31], v23 offset0:33 offset1:41
	ds_read2_b32 v[32:33], v23 offset1:8
	ds_read2_b32 v[34:35], v23 offset0:66 offset1:74
	ds_read2_b32 v[36:37], v23 offset0:99 offset1:107
	ds_read2_b32 v[38:39], v23 offset0:132 offset1:140
	ds_read2_b32 v[40:41], v23 offset0:165 offset1:173
	ds_read2_b32 v[42:43], v23 offset0:198 offset1:206
	ds_read2_b32 v[44:45], v23 offset0:231 offset1:239
	v_lshlrev_b32_e32 v0, 1, v15
	v_lshl_add_u64 v[28:29], v[8:9], 0, v[0:1]
	v_or_b32_e32 v0, v21, v22
	v_lshlrev_b32_e32 v0, 11, v0
	v_lshl_add_u64 v[46:47], v[28:29], 0, v[0:1]
	v_or_b32_e32 v0, v21, v24
	s_waitcnt lgkmcnt(6)
	v_cvt_pk_bf16_f32 v16, v32, v30
	s_waitcnt lgkmcnt(4)
	v_cvt_pk_bf16_f32 v17, v34, v36
	s_waitcnt lgkmcnt(2)
	v_cvt_pk_bf16_f32 v18, v38, v40
	s_waitcnt lgkmcnt(0)
	v_cvt_pk_bf16_f32 v19, v42, v44
	v_lshlrev_b32_e32 v0, 11, v0
	global_store_dwordx4 v[46:47], v[16:19], off
	s_nop 1
	v_cvt_pk_bf16_f32 v16, v33, v31
	v_cvt_pk_bf16_f32 v17, v35, v37
	v_cvt_pk_bf16_f32 v18, v39, v41
	v_cvt_pk_bf16_f32 v19, v43, v45
	v_lshl_add_u64 v[30:31], v[28:29], 0, v[0:1]
	global_store_dwordx4 v[30:31], v[16:19], off
	ds_read2_b32 v[30:31], v23 offset0:49 offset1:57
	ds_read2_b32 v[32:33], v23 offset0:16 offset1:24
	ds_read2_b32 v[34:35], v23 offset0:82 offset1:90
	ds_read2_b32 v[36:37], v23 offset0:115 offset1:123
	ds_read2_b32 v[38:39], v23 offset0:148 offset1:156
	ds_read2_b32 v[40:41], v23 offset0:181 offset1:189
	ds_read2_b32 v[42:43], v23 offset0:214 offset1:222
	ds_read2_b32 v[44:45], v23 offset0:247 offset1:255
	v_or_b32_e32 v0, v21, v25
	v_lshlrev_b32_e32 v0, 11, v0
	v_lshl_add_u64 v[46:47], v[28:29], 0, v[0:1]
	v_or_b32_e32 v0, v21, v26
	s_waitcnt lgkmcnt(6)
	v_cvt_pk_bf16_f32 v16, v32, v30
	s_waitcnt lgkmcnt(4)
	v_cvt_pk_bf16_f32 v17, v34, v36
	s_waitcnt lgkmcnt(2)
	v_cvt_pk_bf16_f32 v18, v38, v40
	s_waitcnt lgkmcnt(0)
	v_cvt_pk_bf16_f32 v19, v42, v44
	v_lshlrev_b32_e32 v0, 11, v0
	global_store_dwordx4 v[46:47], v[16:19], off
	v_lshl_add_u64 v[20:21], v[28:29], 0, v[0:1]
	s_nop 0
	v_cvt_pk_bf16_f32 v16, v33, v31
	v_cvt_pk_bf16_f32 v17, v35, v37
	v_cvt_pk_bf16_f32 v18, v39, v41
	v_cvt_pk_bf16_f32 v19, v43, v45
	global_store_dwordx4 v[20:21], v[16:19], off
	s_waitcnt lgkmcnt(0)

; __device__ __forceinline__ void transpose_item(const float* W, int K, int N, bf16_t* WT, LAS float* scr, int item, int lane) {
;     const int nblk = N / 32, kb = item / nblk, nb = item % nblk, k0 = 64 * kb, n0 = 32 * nb;
; #pragma unroll 8
;     for (int i = 0; i < 32; ++i) { const int kk = 2 * i + (lane >> 5); scr[kk * 33 + (lane & 31)] = W[(size_t)(k0 + kk) * N + n0 + (lane & 31)]; }
;     asm volatile("s_waitcnt lgkmcnt(0)" ::: "memory");
; __device__ __forceinline__ void convert_weights(const Params& p, int l, unsigned char* lds) {
;     ...
;         if (r < 3 * I_BR) { const int n = r / I_BR; transpose_item(p.in[I_WBR] + ((size_t)l * 3 + n) * 512 * 1024, 512, 1024, wbr + (size_t)n * 1024 * 512, scr, r % I_BR, lane); continue; } r -= 3 * I_BR;
.Lcw_gather2:
	s_lshl_b32 s13, s10, 1
	s_lshl_b32 s12, s2, 1
	v_or_b32_e32 v64, s13, v20
	v_or_b32_e32 v65, s12, v5
	v_or_b32_e32 v66, s13, v2
	v_or_b32_e32 v67, s12, v3
	v_add_u32_e32 v72, 0, v64
	v_mov_b32_e32 v73, v1
	v_lshlrev_b64 v[68:69], 12, v[72:73]
	v_lshl_add_u64 v[68:69], v[18:19], 0, v[68:69]
	global_load_dword v48, v[68:69], off
	v_add_u32_e32 v72, 0, v65
	v_mov_b32_e32 v73, v1
	v_lshlrev_b64 v[70:71], 12, v[72:73]
	v_lshl_add_u64 v[70:71], v[18:19], 0, v[70:71]
	global_load_dword v49, v[70:71], off
	v_add_u32_e32 v72, 4, v64
	v_mov_b32_e32 v73, v1
	v_lshlrev_b64 v[68:69], 12, v[72:73]
	v_lshl_add_u64 v[68:69], v[18:19], 0, v[68:69]
	global_load_dword v50, v[68:69], off
	v_add_u32_e32 v72, 4, v65
	v_mov_b32_e32 v73, v1
	v_lshlrev_b64 v[70:71], 12, v[72:73]
	v_lshl_add_u64 v[70:71], v[18:19], 0, v[70:71]
	global_load_dword v51, v[70:71], off
	v_add_u32_e32 v72, 8, v64
	v_mov_b32_e32 v73, v1
	v_lshlrev_b64 v[68:69], 12, v[72:73]
	v_lshl_add_u64 v[68:69], v[18:19], 0, v[68:69]
	global_load_dword v52, v[68:69], off
	v_add_u32_e32 v72, 8, v65
	v_mov_b32_e32 v73, v1
	v_lshlrev_b64 v[70:71], 12, v[72:73]
	v_lshl_add_u64 v[70:71], v[18:19], 0, v[70:71]
	global_load_dword v53, v[70:71], off
	v_add_u32_e32 v72, 12, v64
	v_mov_b32_e32 v73, v1
	v_lshlrev_b64 v[68:69], 12, v[72:73]
	v_lshl_add_u64 v[68:69], v[18:19], 0, v[68:69]
	global_load_dword v54, v[68:69], off
	v_add_u32_e32 v72, 12, v65
	v_mov_b32_e32 v73, v1
	v_lshlrev_b64 v[70:71], 12, v[72:73]
	v_lshl_add_u64 v[70:71], v[18:19], 0, v[70:71]
	global_load_dword v55, v[70:71], off
	v_add_u32_e32 v72, 16, v64
	v_mov_b32_e32 v73, v1
	v_lshlrev_b64 v[68:69], 12, v[72:73]
	v_lshl_add_u64 v[68:69], v[18:19], 0, v[68:69]
	global_load_dword v56, v[68:69], off
	v_add_u32_e32 v72, 16, v65
	v_mov_b32_e32 v73, v1
	v_lshlrev_b64 v[70:71], 12, v[72:73]
	v_lshl_add_u64 v[70:71], v[18:19], 0, v[70:71]
	global_load_dword v57, v[70:71], off
	v_add_u32_e32 v72, 20, v64
	v_mov_b32_e32 v73, v1
	v_lshlrev_b64 v[68:69], 12, v[72:73]
	v_lshl_add_u64 v[68:69], v[18:19], 0, v[68:69]
	global_load_dword v58, v[68:69], off
	v_add_u32_e32 v72, 20, v65
	v_mov_b32_e32 v73, v1
	v_lshlrev_b64 v[70:71], 12, v[72:73]
	v_lshl_add_u64 v[70:71], v[18:19], 0, v[70:71]
	global_load_dword v59, v[70:71], off
	v_add_u32_e32 v72, 24, v64
	v_mov_b32_e32 v73, v1
	v_lshlrev_b64 v[68:69], 12, v[72:73]
	v_lshl_add_u64 v[68:69], v[18:19], 0, v[68:69]
	global_load_dword v60, v[68:69], off
	v_add_u32_e32 v72, 24, v65
	v_mov_b32_e32 v73, v1
	v_lshlrev_b64 v[70:71], 12, v[72:73]
	v_lshl_add_u64 v[70:71], v[18:19], 0, v[70:71]
	global_load_dword v61, v[70:71], off
	v_add_u32_e32 v72, 28, v64
	v_mov_b32_e32 v73, v1
	v_lshlrev_b64 v[68:69], 12, v[72:73]
	v_lshl_add_u64 v[68:69], v[18:19], 0, v[68:69]
	global_load_dword v62, v[68:69], off
	v_add_u32_e32 v72, 28, v65
	v_mov_b32_e32 v73, v1
	v_lshlrev_b64 v[70:71], 12, v[72:73]
	v_lshl_add_u64 v[70:71], v[18:19], 0, v[70:71]
	global_load_dword v63, v[70:71], off
	v_add_u32_e32 v72, 0, v66
	v_mad_u64_u32 v[68:69], s[14:15], v72, s91, v[4:5]
	s_waitcnt vmcnt(15)
	ds_write_b32 v68, v48
	v_add_u32_e32 v72, 0, v67
	v_mad_u64_u32 v[70:71], s[14:15], v72, s91, v[4:5]
	s_waitcnt vmcnt(14)
	ds_write_b32 v70, v49
	v_add_u32_e32 v72, 4, v66
	v_mad_u64_u32 v[68:69], s[14:15], v72, s91, v[4:5]
	s_waitcnt vmcnt(13)
	ds_write_b32 v68, v50
	v_add_u32_e32 v72, 4, v67
	v_mad_u64_u32 v[70:71], s[14:15], v72, s91, v[4:5]
	s_waitcnt vmcnt(12)
	ds_write_b32 v70, v51
	v_add_u32_e32 v72, 8, v66
	v_mad_u64_u32 v[68:69], s[14:15], v72, s91, v[4:5]
	s_waitcnt vmcnt(11)
	ds_write_b32 v68, v52
	v_add_u32_e32 v72, 8, v67
	v_mad_u64_u32 v[70:71], s[14:15], v72, s91, v[4:5]
	s_waitcnt vmcnt(10)
	ds_write_b32 v70, v53
	v_add_u32_e32 v72, 12, v66
	v_mad_u64_u32 v[68:69], s[14:15], v72, s91, v[4:5]
	s_waitcnt vmcnt(9)
	ds_write_b32 v68, v54
	v_add_u32_e32 v72, 12, v67
	v_mad_u64_u32 v[70:71], s[14:15], v72, s91, v[4:5]
	s_waitcnt vmcnt(8)
	ds_write_b32 v70, v55
	v_add_u32_e32 v72, 16, v66
	v_mad_u64_u32 v[68:69], s[14:15], v72, s91, v[4:5]
	s_waitcnt vmcnt(7)
	ds_write_b32 v68, v56
	v_add_u32_e32 v72, 16, v67
	v_mad_u64_u32 v[70:71], s[14:15], v72, s91, v[4:5]
	s_waitcnt vmcnt(6)
	ds_write_b32 v70, v57
	v_add_u32_e32 v72, 20, v66
	v_mad_u64_u32 v[68:69], s[14:15], v72, s91, v[4:5]
	s_waitcnt vmcnt(5)
	ds_write_b32 v68, v58
	v_add_u32_e32 v72, 20, v67
	v_mad_u64_u32 v[70:71], s[14:15], v72, s91, v[4:5]
	s_waitcnt vmcnt(4)
	ds_write_b32 v70, v59
	v_add_u32_e32 v72, 24, v66
	v_mad_u64_u32 v[68:69], s[14:15], v72, s91, v[4:5]
	s_waitcnt vmcnt(3)
	ds_write_b32 v68, v60
	v_add_u32_e32 v72, 24, v67
	v_mad_u64_u32 v[70:71], s[14:15], v72, s91, v[4:5]
	s_waitcnt vmcnt(2)
	ds_write_b32 v70, v61
	v_add_u32_e32 v72, 28, v66
	v_mad_u64_u32 v[68:69], s[14:15], v72, s91, v[4:5]
	s_waitcnt vmcnt(1)
	ds_write_b32 v68, v62
	v_add_u32_e32 v72, 28, v67
	v_mad_u64_u32 v[70:71], s[14:15], v72, s91, v[4:5]
	s_waitcnt vmcnt(0)
	ds_write_b32 v70, v63
	s_add_i32 s10, s10, 16
	s_add_i32 s2, s2, 16
	s_add_i32 s11, s11, -16
	s_cmp_lg_u32 s11, 0
	s_cbranch_scc1 .Lcw_gather2
; #define LAS __attribute__((address_space(3)))
; __device__ __forceinline__ unsigned pk2(float lo, float hi) { f32x2 v = {lo, hi}; hbf16x2 b = __builtin_convertvector(v, hbf16x2); return __builtin_bit_cast(unsigned, b); }
; __device__ __forceinline__ void transpose_item(const float* W, int K, int N, bf16_t* WT, LAS float* scr, int item, int lane) {
;     ...
;     const int c = lane & 7;
; #pragma unroll
;     for (int j = 0; j < 4; ++j) { const int n = (lane >> 3) + 8 * j; const LAS float* s = scr + (8 * c) * 33 + n;
;         u32x4 o; o.x = pk2(s[0 * 33], s[1 * 33]); o.y = pk2(s[2 * 33], s[3 * 33]); o.z = pk2(s[4 * 33], s[5 * 33]); o.w = pk2(s[6 * 33], s[7 * 33]);
;         *(u32x4*)(WT + (size_t)(n0 + n) * K + k0 + 8 * c) = o; }
;     asm volatile("s_waitcnt lgkmcnt(0)" ::: "memory");
; __device__ __forceinline__ void convert_weights(const Params& p, int l, unsigned char* lds) {
;     ...
;         if (r < 3 * I_BR) { const int n = r / I_BR; transpose_item(p.in[I_WBR] + ((size_t)l * 3 + n) * 512 * 1024, 512, 1024, wbr + (size_t)n * 1024 * 512, scr, r % I_BR, lane); continue; } r -= 3 * I_BR;
	v_mov_b32_e32 v17, v1
	v_readlane_b32 s10, v250, 41
	v_lshlrev_b64 v[16:17], 20, v[16:17]
	v_readlane_b32 s11, v250, 42
	s_waitcnt lgkmcnt(0)
	v_lshlrev_b32_e32 v0, 1, v27
	ds_read2_b32 v[30:31], v23 offset0:33 offset1:41
	ds_read2_b32 v[32:33], v23 offset1:8
	v_lshl_add_u64 v[16:17], s[10:11], 0, v[16:17]
	ds_read2_b32 v[34:35], v23 offset0:66 offset1:74
	ds_read2_b32 v[36:37], v23 offset0:99 offset1:107
	ds_read2_b32 v[38:39], v23 offset0:132 offset1:140
	ds_read2_b32 v[40:41], v23 offset0:165 offset1:173
	ds_read2_b32 v[42:43], v23 offset0:198 offset1:206
	ds_read2_b32 v[44:45], v23 offset0:231 offset1:239
	v_lshl_add_u64 v[16:17], v[16:17], 0, v[0:1]
	v_lshlrev_b32_e32 v0, 1, v6
	v_lshl_add_u64 v[28:29], v[16:17], 0, v[0:1]
	v_or_b32_e32 v0, v21, v22
	v_lshlrev_b32_e32 v0, 10, v0
	v_lshl_add_u64 v[46:47], v[28:29], 0, v[0:1]
	v_or_b32_e32 v0, v21, v24
	s_waitcnt lgkmcnt(6)
	v_cvt_pk_bf16_f32 v16, v32, v30
	s_waitcnt lgkmcnt(4)
	v_cvt_pk_bf16_f32 v17, v34, v36
	s_waitcnt lgkmcnt(2)
	v_cvt_pk_bf16_f32 v18, v38, v40
	s_waitcnt lgkmcnt(0)
	v_cvt_pk_bf16_f32 v19, v42, v44
	v_lshlrev_b32_e32 v0, 10, v0
	global_store_dwordx4 v[46:47], v[16:19], off
	v_readlane_b32 s16, v254, 46
	s_nop 0
	v_cvt_pk_bf16_f32 v16, v33, v31
	v_cvt_pk_bf16_f32 v17, v35, v37
	v_cvt_pk_bf16_f32 v18, v39, v41
	v_cvt_pk_bf16_f32 v19, v43, v45
	v_lshl_add_u64 v[30:31], v[28:29], 0, v[0:1]
	global_store_dwordx4 v[30:31], v[16:19], off
	ds_read2_b32 v[30:31], v23 offset0:49 offset1:57
	ds_read2_b32 v[32:33], v23 offset0:16 offset1:24
	ds_read2_b32 v[34:35], v23 offset0:82 offset1:90
	ds_read2_b32 v[36:37], v23 offset0:115 offset1:123
	ds_read2_b32 v[38:39], v23 offset0:148 offset1:156
	ds_read2_b32 v[40:41], v23 offset0:181 offset1:189
	ds_read2_b32 v[42:43], v23 offset0:214 offset1:222
	ds_read2_b32 v[44:45], v23 offset0:247 offset1:255
	v_or_b32_e32 v0, v21, v25
	v_lshlrev_b32_e32 v0, 10, v0
	v_lshl_add_u64 v[46:47], v[28:29], 0, v[0:1]
	v_or_b32_e32 v0, v21, v26
	s_waitcnt lgkmcnt(6)
	v_cvt_pk_bf16_f32 v16, v32, v30
	s_waitcnt lgkmcnt(4)
	v_cvt_pk_bf16_f32 v17, v34, v36
	s_waitcnt lgkmcnt(2)
	v_cvt_pk_bf16_f32 v18, v38, v40
	s_waitcnt lgkmcnt(0)
	v_cvt_pk_bf16_f32 v19, v42, v44
	v_lshlrev_b32_e32 v0, 10, v0
	global_store_dwordx4 v[46:47], v[16:19], off
	v_lshl_add_u64 v[20:21], v[28:29], 0, v[0:1]
	s_nop 0
	v_cvt_pk_bf16_f32 v16, v33, v31
	v_cvt_pk_bf16_f32 v17, v35, v37
	v_cvt_pk_bf16_f32 v18, v39, v41
	v_cvt_pk_bf16_f32 v19, v43, v45
	global_store_dwordx4 v[20:21], v[16:19], off
	s_waitcnt lgkmcnt(0)

; #define LAS __attribute__((address_space(3)))
; __device__ __forceinline__ unsigned pk2(float lo, float hi) { f32x2 v = {lo, hi}; hbf16x2 b = __builtin_convertvector(v, hbf16x2); return __builtin_bit_cast(unsigned, b); }
; __device__ __forceinline__ void transpose_item(const float* W, int K, int N, bf16_t* WT, LAS float* scr, int item, int lane) {
;     const int nblk = N / 32, kb = item / nblk, nb = item % nblk, k0 = 64 * kb, n0 = 32 * nb;
; #pragma unroll 8
;     for (int i = 0; i < 32; ++i) { const int kk = 2 * i + (lane >> 5); scr[kk * 33 + (lane & 31)] = W[(size_t)(k0 + kk) * N + n0 + (lane & 31)]; }
;     asm volatile("s_waitcnt lgkmcnt(0)" ::: "memory");
;     const int c = lane & 7;
; #pragma unroll
;     for (int j = 0; j < 4; ++j) { const int n = (lane >> 3) + 8 * j; const LAS float* s = scr + (8 * c) * 33 + n;
;         u32x4 o; o.x = pk2(s[0 * 33], s[1 * 33]); o.y = pk2(s[2 * 33], s[3 * 33]); o.z = pk2(s[4 * 33], s[5 * 33]); o.w = pk2(s[6 * 33], s[7 * 33]);
;         *(u32x4*)(WT + (size_t)(n0 + n) * K + k0 + 8 * c) = o; }
;     asm volatile("s_waitcnt lgkmcnt(0)" ::: "memory");
; __device__ __forceinline__ void convert_weights(const Params& p, int l, unsigned char* lds) {
;     ...
;         if (r < I_IN) { transpose_item(p.in[I_WIN] + (size_t)l * 1024 * DIN, 1024, DIN, ((r % (DIN / 32)) * 32 < 1792) ? winrw : win2, scr, r, lane); continue; } r -= I_IN;
.Lcw_gather3:
	s_lshl_b32 s11, s8, 1
	s_lshl_b32 s10, s2, 1
	v_or_b32_e32 v64, s11, v0
	v_or_b32_e32 v65, s10, v5
	v_or_b32_e32 v66, s11, v2
	v_or_b32_e32 v67, s10, v3
	v_add_u32_e32 v72, 0, v64
	v_mad_i64_i32 v[68:69], s[12:13], v72, s81, v[20:21]
	global_load_dword v48, v[68:69], off
	v_add_u32_e32 v72, 0, v65
	v_mad_i64_i32 v[70:71], s[12:13], v72, s81, v[20:21]
	global_load_dword v49, v[70:71], off
	v_add_u32_e32 v72, 4, v64
	v_mad_i64_i32 v[68:69], s[12:13], v72, s81, v[20:21]
	global_load_dword v50, v[68:69], off
	v_add_u32_e32 v72, 4, v65
	v_mad_i64_i32 v[70:71], s[12:13], v72, s81, v[20:21]
	global_load_dword v51, v[70:71], off
	v_add_u32_e32 v72, 8, v64
	v_mad_i64_i32 v[68:69], s[12:13], v72, s81, v[20:21]
	global_load_dword v52, v[68:69], off
	v_add_u32_e32 v72, 8, v65
	v_mad_i64_i32 v[70:71], s[12:13], v72, s81, v[20:21]
	global_load_dword v53, v[70:71], off
	v_add_u32_e32 v72, 12, v64
	v_mad_i64_i32 v[68:69], s[12:13], v72, s81, v[20:21]
	global_load_dword v54, v[68:69], off
	v_add_u32_e32 v72, 12, v65
	v_mad_i64_i32 v[70:71], s[12:13], v72, s81, v[20:21]
	global_load_dword v55, v[70:71], off
	v_add_u32_e32 v72, 16, v64
	v_mad_i64_i32 v[68:69], s[12:13], v72, s81, v[20:21]
	global_load_dword v56, v[68:69], off
	v_add_u32_e32 v72, 16, v65
	v_mad_i64_i32 v[70:71], s[12:13], v72, s81, v[20:21]
	global_load_dword v57, v[70:71], off
	v_add_u32_e32 v72, 20, v64
	v_mad_i64_i32 v[68:69], s[12:13], v72, s81, v[20:21]
	global_load_dword v58, v[68:69], off
	v_add_u32_e32 v72, 20, v65
	v_mad_i64_i32 v[70:71], s[12:13], v72, s81, v[20:21]
	global_load_dword v59, v[70:71], off
	v_add_u32_e32 v72, 24, v64
	v_mad_i64_i32 v[68:69], s[12:13], v72, s81, v[20:21]
	global_load_dword v60, v[68:69], off
	v_add_u32_e32 v72, 24, v65
	v_mad_i64_i32 v[70:71], s[12:13], v72, s81, v[20:21]
	global_load_dword v61, v[70:71], off
	v_add_u32_e32 v72, 28, v64
	v_mad_i64_i32 v[68:69], s[12:13], v72, s81, v[20:21]
	global_load_dword v62, v[68:69], off
	v_add_u32_e32 v72, 28, v65
	v_mad_i64_i32 v[70:71], s[12:13], v72, s81, v[20:21]
	global_load_dword v63, v[70:71], off
	v_add_u32_e32 v72, 0, v66
	v_mad_u64_u32 v[68:69], s[12:13], v72, s91, v[4:5]
	s_waitcnt vmcnt(15)
	ds_write_b32 v68, v48
	v_add_u32_e32 v72, 0, v67
	v_mad_u64_u32 v[70:71], s[12:13], v72, s91, v[4:5]
	s_waitcnt vmcnt(14)
	ds_write_b32 v70, v49
	v_add_u32_e32 v72, 4, v66
	v_mad_u64_u32 v[68:69], s[12:13], v72, s91, v[4:5]
	s_waitcnt vmcnt(13)
	ds_write_b32 v68, v50
	v_add_u32_e32 v72, 4, v67
	v_mad_u64_u32 v[70:71], s[12:13], v72, s91, v[4:5]
	s_waitcnt vmcnt(12)
	ds_write_b32 v70, v51
	v_add_u32_e32 v72, 8, v66
	v_mad_u64_u32 v[68:69], s[12:13], v72, s91, v[4:5]
	s_waitcnt vmcnt(11)
	ds_write_b32 v68, v52
	v_add_u32_e32 v72, 8, v67
	v_mad_u64_u32 v[70:71], s[12:13], v72, s91, v[4:5]
	s_waitcnt vmcnt(10)
	ds_write_b32 v70, v53
	v_add_u32_e32 v72, 12, v66
	v_mad_u64_u32 v[68:69], s[12:13], v72, s91, v[4:5]
	s_waitcnt vmcnt(9)
	ds_write_b32 v68, v54
	v_add_u32_e32 v72, 12, v67
	v_mad_u64_u32 v[70:71], s[12:13], v72, s91, v[4:5]
	s_waitcnt vmcnt(8)
	ds_write_b32 v70, v55
	v_add_u32_e32 v72, 16, v66
	v_mad_u64_u32 v[68:69], s[12:13], v72, s91, v[4:5]
	s_waitcnt vmcnt(7)
	ds_write_b32 v68, v56
	v_add_u32_e32 v72, 16, v67
	v_mad_u64_u32 v[70:71], s[12:13], v72, s91, v[4:5]
	s_waitcnt vmcnt(6)
	ds_write_b32 v70, v57
	v_add_u32_e32 v72, 20, v66
	v_mad_u64_u32 v[68:69], s[12:13], v72, s91, v[4:5]
	s_waitcnt vmcnt(5)
	ds_write_b32 v68, v58
	v_add_u32_e32 v72, 20, v67
	v_mad_u64_u32 v[70:71], s[12:13], v72, s91, v[4:5]
	s_waitcnt vmcnt(4)
	ds_write_b32 v70, v59
	v_add_u32_e32 v72, 24, v66
	v_mad_u64_u32 v[68:69], s[12:13], v72, s91, v[4:5]
	s_waitcnt vmcnt(3)
	ds_write_b32 v68, v60
	v_add_u32_e32 v72, 24, v67
	v_mad_u64_u32 v[70:71], s[12:13], v72, s91, v[4:5]
	s_waitcnt vmcnt(2)
	ds_write_b32 v70, v61
	v_add_u32_e32 v72, 28, v66
	v_mad_u64_u32 v[68:69], s[12:13], v72, s91, v[4:5]
	s_waitcnt vmcnt(1)
	ds_write_b32 v68, v62
	v_add_u32_e32 v72, 28, v67
	v_mad_u64_u32 v[70:71], s[12:13], v72, s91, v[4:5]
	s_waitcnt vmcnt(0)
	ds_write_b32 v70, v63
	s_add_i32 s8, s8, 16
	s_add_i32 s2, s2, 16
	s_add_i32 s9, s9, -16
	s_cmp_lg_u32 s9, 0
	s_cbranch_scc1 .Lcw_gather3
	s_waitcnt lgkmcnt(0)
	v_cmp_gt_i32_e32 vcc, 56, v15
	ds_read2_b32 v[30:31], v23 offset0:33 offset1:41
	ds_read2_b32 v[32:33], v23 offset1:8
	ds_read2_b32 v[34:35], v23 offset0:66 offset1:74
	ds_read2_b32 v[36:37], v23 offset0:99 offset1:107
	ds_read2_b32 v[38:39], v23 offset0:132 offset1:140
	ds_read2_b32 v[40:41], v23 offset0:165 offset1:173
	ds_read2_b32 v[42:43], v23 offset0:198 offset1:206
	ds_read2_b32 v[44:45], v23 offset0:231 offset1:239
	v_cndmask_b32_e32 v0, v235, v236, vcc
	v_lshl_add_u64 v[20:21], s[72:73], 0, v[0:1]
	v_ashrrev_i32_e32 v19, 31, v18
	v_or_b32_e32 v46, v16, v22
	v_lshl_add_u64 v[18:19], v[18:19], 1, v[20:21]
	v_lshlrev_b32_e32 v0, 1, v6
	v_ashrrev_i32_e32 v47, 31, v46
	v_lshl_add_u64 v[28:29], v[18:19], 0, v[0:1]
	v_lshlrev_b64 v[46:47], 11, v[46:47]
	s_waitcnt lgkmcnt(6)
	v_cvt_pk_bf16_f32 v18, v32, v30
	s_waitcnt lgkmcnt(4)
	v_cvt_pk_bf16_f32 v19, v34, v36
	s_waitcnt lgkmcnt(2)
	v_cvt_pk_bf16_f32 v20, v38, v40
	s_waitcnt lgkmcnt(0)
	v_cvt_pk_bf16_f32 v21, v42, v44
	v_lshl_add_u64 v[46:47], v[28:29], 0, v[46:47]
	v_or_b32_e32 v30, v16, v24
	global_store_dwordx4 v[46:47], v[18:21], off
	v_or_b32_e32 v46, v16, v25
	v_ashrrev_i32_e32 v47, 31, v46
	v_cvt_pk_bf16_f32 v18, v33, v31
	v_ashrrev_i32_e32 v31, 31, v30
	v_lshlrev_b64 v[30:31], 11, v[30:31]
	v_cvt_pk_bf16_f32 v19, v35, v37
	v_cvt_pk_bf16_f32 v20, v39, v41
	v_cvt_pk_bf16_f32 v21, v43, v45
	v_lshl_add_u64 v[30:31], v[28:29], 0, v[30:31]
	global_store_dwordx4 v[30:31], v[18:21], off
	ds_read2_b32 v[30:31], v23 offset0:49 offset1:57
	ds_read2_b32 v[32:33], v23 offset0:16 offset1:24
	ds_read2_b32 v[34:35], v23 offset0:82 offset1:90
	ds_read2_b32 v[36:37], v23 offset0:115 offset1:123
	ds_read2_b32 v[38:39], v23 offset0:148 offset1:156
	ds_read2_b32 v[40:41], v23 offset0:181 offset1:189
	ds_read2_b32 v[42:43], v23 offset0:214 offset1:222
	ds_read2_b32 v[44:45], v23 offset0:247 offset1:255
	v_or_b32_e32 v16, v16, v26
	v_lshlrev_b64 v[46:47], 11, v[46:47]
	v_ashrrev_i32_e32 v17, 31, v16
	s_waitcnt lgkmcnt(6)
	v_cvt_pk_bf16_f32 v18, v32, v30
	s_waitcnt lgkmcnt(4)
	v_cvt_pk_bf16_f32 v19, v34, v36
	s_waitcnt lgkmcnt(2)
	v_cvt_pk_bf16_f32 v20, v38, v40
	s_waitcnt lgkmcnt(0)
	v_cvt_pk_bf16_f32 v21, v42, v44
	v_lshl_add_u64 v[46:47], v[28:29], 0, v[46:47]
	v_lshlrev_b64 v[16:17], 11, v[16:17]
	global_store_dwordx4 v[46:47], v[18:21], off
	v_lshl_add_u64 v[16:17], v[28:29], 0, v[16:17]
	s_nop 0
	v_cvt_pk_bf16_f32 v18, v33, v31
	v_cvt_pk_bf16_f32 v19, v35, v37
	v_cvt_pk_bf16_f32 v20, v39, v41
	v_cvt_pk_bf16_f32 v21, v43, v45
	global_store_dwordx4 v[16:17], v[18:21], off
	s_waitcnt lgkmcnt(0)
	s_branch .LBB0_1261
